# resid+norm epilogue part 1: residual loads batched 16 deep instead of 2-at-a-time with vmcnt(0)
# speedup vs baseline: 1.0408x; 1.0408x over previous
.LBB0_532:
	v_and_b32_e32 v130, 64, v209
	s_lshl_b32 s6, s81, 8
	v_xor_b32_e32 v0, 16, v209
	v_add_u32_e32 v130, 64, v130
	s_add_i32 s6, s6, s47
	v_cmp_lt_i32_e32 vcc, v0, v130
	v_xor_b32_e32 v131, 32, v209
	s_lshl_b32 s0, s34, 5
	v_add_u32_e32 v194, s6, v145
	s_lshl_b32 s6, s84, 8
	v_cndmask_b32_e32 v0, v209, v0, vcc
	v_cmp_lt_i32_e32 vcc, v131, v130
	s_or_b32 s0, s6, s0
	v_ashrrev_i32_e32 v195, 31, v194
	v_cndmask_b32_e32 v130, v209, v131, vcc
	v_lshl_or_b32 v166, v144, 3, s0
	v_lshlrev_b32_e32 v172, 2, v130
	v_lshlrev_b64 v[130:131], 12, v[194:195]
	v_ashrrev_i32_e32 v167, 31, v166
	v_lshl_add_u64 v[130:131], s[16:17], 0, v[130:131]
	v_lshl_add_u64 v[138:139], v[166:167], 2, v[130:131]
	s_barrier
	v_lshlrev_b32_e32 v0, 2, v0
	v_mov_b32_e32 v251, v172
	v_cmp_eq_u32_e32 vcc, 0, v144
	v_lshlrev_b32_e32 v200, 12, v194
	v_lshl_add_u32 v200, v166, 2, v200
	s_mov_b64 s[100:101], s[16:17]
	global_load_dwordx4 v[150:153], v200, s[100:101]
	global_load_dwordx4 v[146:149], v200, s[100:101] offset:16
	global_load_dwordx4 v[154:157], v200, s[100:101] offset:512
	global_load_dwordx4 v[158:161], v200, s[100:101] offset:528
	s_add_u32 s100, s16, 0x10000
	s_addc_u32 s101, s17, 0
	global_load_dwordx4 v[134:137], v200, s[100:101]
	global_load_dwordx4 v[130:133], v200, s[100:101] offset:16
	global_load_dwordx4 v[138:141], v200, s[100:101] offset:512
	global_load_dwordx4 v[142:145], v200, s[100:101] offset:528
	s_add_u32 s100, s16, 0x20000
	s_addc_u32 s101, s17, 0
	global_load_dwordx4 v[210:213], v200, s[100:101]
	global_load_dwordx4 v[214:217], v200, s[100:101] offset:16
	global_load_dwordx4 v[218:221], v200, s[100:101] offset:512
	global_load_dwordx4 v[222:225], v200, s[100:101] offset:528
	s_add_u32 s100, s16, 0x30000
	s_addc_u32 s101, s17, 0
	global_load_dwordx4 v[226:229], v200, s[100:101]
	global_load_dwordx4 v[230:233], v200, s[100:101] offset:16
	global_load_dwordx4 v[234:237], v200, s[100:101] offset:512
	global_load_dwordx4 v[238:241], v200, s[100:101] offset:528
	s_lshl_b32 s6, s84, 2
	s_ashr_i32 s7, s6, 31
	s_lshl_b64 s[6:7], s[6:7], 2
	s_add_u32 s0, s22, s6
	s_addc_u32 s7, s23, s7
	s_lshl_b32 s6, s34, 2
	s_add_u32 s6, s0, s6
	s_addc_u32 s7, s7, 0
	v_readlane_b32 s28, v254, 39
	s_mov_b32 s98, s36
	s_mov_b32 s83, 0x800000
	v_readlane_b32 s29, v254, 40
	v_readlane_b32 s48, v254, 41
	s_mov_b64 s[34:35], s[50:51]
	v_readlane_b32 s49, v254, 42
	s_waitcnt vmcnt(12)
	v_pk_fma_f32 v[150:151], s[18:19], v[126:127], v[150:151]
	v_pk_fma_f32 v[152:153], s[24:25], v[128:129], v[152:153]
	v_pk_fma_f32 v[146:147], s[18:19], v[122:123], v[146:147]
	v_pk_fma_f32 v[148:149], s[24:25], v[124:125], v[148:149]
	v_pk_fma_f32 v[154:155], s[18:19], v[118:119], v[154:155]
	v_pk_fma_f32 v[156:157], s[24:25], v[120:121], v[156:157]
	v_pk_fma_f32 v[158:159], s[18:19], v[114:115], v[158:159]
	v_pk_fma_f32 v[160:161], s[24:25], v[116:117], v[160:161]
	v_mul_f32_e32 v202, v153, v153
	v_mul_f32_e32 v201, v151, v151
	v_fmac_f32_e32 v201, v150, v150
	v_fmac_f32_e32 v202, v152, v152
	v_add_f32_e32 v201, v201, v202
	v_mul_f32_e32 v206, v149, v149
	v_mul_f32_e32 v203, v147, v147
	v_fmac_f32_e32 v203, v146, v146
	v_fmac_f32_e32 v206, v148, v148
	v_add_f32_e32 v203, v203, v206
	v_add_f32_e32 v201, v201, v203
	v_mul_f32_e32 v206, v157, v157
	v_mul_f32_e32 v203, v155, v155
	v_fmac_f32_e32 v203, v154, v154
	v_fmac_f32_e32 v206, v156, v156
	v_add_f32_e32 v203, v203, v206
	v_mul_f32_e32 v206, v161, v161
	v_mul_f32_e32 v202, v159, v159
	v_fmac_f32_e32 v202, v158, v158
	v_fmac_f32_e32 v206, v160, v160
	v_add_f32_e32 v202, v202, v206
	v_add_f32_e32 v203, v203, v202
	v_add_f32_e32 v242, v201, v203
	s_add_u32 s100, s16, 0x80000
	s_addc_u32 s101, s17, 0
	global_load_dwordx4 v[114:117], v200, s[100:101]
	global_load_dwordx4 v[118:121], v200, s[100:101] offset:16
	global_load_dwordx4 v[122:125], v200, s[100:101] offset:512
	global_load_dwordx4 v[126:129], v200, s[100:101] offset:528
	s_waitcnt vmcnt(12)
	v_pk_fma_f32 v[134:135], s[18:19], v[110:111], v[134:135]
	v_pk_fma_f32 v[136:137], s[24:25], v[112:113], v[136:137]
	v_pk_fma_f32 v[130:131], s[18:19], v[106:107], v[130:131]
	v_pk_fma_f32 v[132:133], s[24:25], v[108:109], v[132:133]
	v_pk_fma_f32 v[138:139], s[18:19], v[102:103], v[138:139]
	v_pk_fma_f32 v[140:141], s[24:25], v[104:105], v[140:141]
	v_pk_fma_f32 v[142:143], s[18:19], v[98:99], v[142:143]
	v_pk_fma_f32 v[144:145], s[24:25], v[100:101], v[144:145]
	v_mul_f32_e32 v202, v137, v137
	v_mul_f32_e32 v201, v135, v135
	v_fmac_f32_e32 v201, v134, v134
	v_fmac_f32_e32 v202, v136, v136
	v_add_f32_e32 v201, v201, v202
	v_mul_f32_e32 v206, v133, v133
	v_mul_f32_e32 v203, v131, v131
	v_fmac_f32_e32 v203, v130, v130
	v_fmac_f32_e32 v206, v132, v132
	v_add_f32_e32 v203, v203, v206
	v_add_f32_e32 v201, v201, v203
	v_mul_f32_e32 v206, v141, v141
	v_mul_f32_e32 v203, v139, v139
	v_fmac_f32_e32 v203, v138, v138
	v_fmac_f32_e32 v206, v140, v140
	v_add_f32_e32 v203, v203, v206
	v_mul_f32_e32 v206, v145, v145
	v_mul_f32_e32 v202, v143, v143
	v_fmac_f32_e32 v202, v142, v142
	v_fmac_f32_e32 v206, v144, v144
	v_add_f32_e32 v202, v202, v206
	v_add_f32_e32 v203, v203, v202
	v_add_f32_e32 v243, v201, v203
	s_add_u32 s100, s16, 0x90000
	s_addc_u32 s101, s17, 0
	global_load_dwordx4 v[98:101], v200, s[100:101]
	global_load_dwordx4 v[102:105], v200, s[100:101] offset:16
	global_load_dwordx4 v[106:109], v200, s[100:101] offset:512
	global_load_dwordx4 v[110:113], v200, s[100:101] offset:528
	s_waitcnt vmcnt(12)
	v_pk_fma_f32 v[86:87], s[18:19], v[86:87], v[210:211]
	v_pk_fma_f32 v[88:89], s[24:25], v[88:89], v[212:213]
	v_pk_fma_f32 v[82:83], s[18:19], v[82:83], v[214:215]
	v_pk_fma_f32 v[84:85], s[24:25], v[84:85], v[216:217]
	v_pk_fma_f32 v[90:91], s[18:19], v[90:91], v[218:219]
	v_pk_fma_f32 v[92:93], s[24:25], v[92:93], v[220:221]
	v_pk_fma_f32 v[94:95], s[18:19], v[94:95], v[222:223]
	v_pk_fma_f32 v[96:97], s[24:25], v[96:97], v[224:225]
	v_mul_f32_e32 v202, v89, v89
	v_mul_f32_e32 v201, v87, v87
	v_fmac_f32_e32 v201, v86, v86
	v_fmac_f32_e32 v202, v88, v88
	v_add_f32_e32 v201, v201, v202
	v_mul_f32_e32 v206, v85, v85
	v_mul_f32_e32 v203, v83, v83
	v_fmac_f32_e32 v203, v82, v82
	v_fmac_f32_e32 v206, v84, v84
	v_add_f32_e32 v203, v203, v206
	v_add_f32_e32 v201, v201, v203
	v_mul_f32_e32 v206, v93, v93
	v_mul_f32_e32 v203, v91, v91
	v_fmac_f32_e32 v203, v90, v90
	v_fmac_f32_e32 v206, v92, v92
	v_add_f32_e32 v203, v203, v206
	v_mul_f32_e32 v206, v97, v97
	v_mul_f32_e32 v202, v95, v95
	v_fmac_f32_e32 v202, v94, v94
	v_fmac_f32_e32 v206, v96, v96
	v_add_f32_e32 v202, v202, v206
	v_add_f32_e32 v203, v203, v202
	v_add_f32_e32 v244, v201, v203
	s_add_u32 s100, s16, 0xa0000
	s_addc_u32 s101, s17, 0
	global_load_dwordx4 v[210:213], v200, s[100:101]
	global_load_dwordx4 v[214:217], v200, s[100:101] offset:16
	global_load_dwordx4 v[218:221], v200, s[100:101] offset:512
	global_load_dwordx4 v[222:225], v200, s[100:101] offset:528
	s_waitcnt vmcnt(12)
	v_pk_fma_f32 v[70:71], s[18:19], v[70:71], v[226:227]
	v_pk_fma_f32 v[72:73], s[24:25], v[72:73], v[228:229]
	v_pk_fma_f32 v[66:67], s[18:19], v[66:67], v[230:231]
	v_pk_fma_f32 v[68:69], s[24:25], v[68:69], v[232:233]
	v_pk_fma_f32 v[74:75], s[18:19], v[74:75], v[234:235]
	v_pk_fma_f32 v[76:77], s[24:25], v[76:77], v[236:237]
	v_pk_fma_f32 v[78:79], s[18:19], v[78:79], v[238:239]
	v_pk_fma_f32 v[80:81], s[24:25], v[80:81], v[240:241]
	v_mul_f32_e32 v202, v73, v73
	v_mul_f32_e32 v201, v71, v71
	v_fmac_f32_e32 v201, v70, v70
	v_fmac_f32_e32 v202, v72, v72
	v_add_f32_e32 v201, v201, v202
	v_mul_f32_e32 v206, v69, v69
	v_mul_f32_e32 v203, v67, v67
	v_fmac_f32_e32 v203, v66, v66
	v_fmac_f32_e32 v206, v68, v68
	v_add_f32_e32 v203, v203, v206
	v_add_f32_e32 v201, v201, v203
	v_mul_f32_e32 v206, v77, v77
	v_mul_f32_e32 v203, v75, v75
	v_fmac_f32_e32 v203, v74, v74
	v_fmac_f32_e32 v206, v76, v76
	v_add_f32_e32 v203, v203, v206
	v_mul_f32_e32 v206, v81, v81
	v_mul_f32_e32 v202, v79, v79
	v_fmac_f32_e32 v202, v78, v78
	v_fmac_f32_e32 v206, v80, v80
	v_add_f32_e32 v202, v202, v206
	v_add_f32_e32 v203, v203, v202
	v_add_f32_e32 v245, v201, v203
	s_add_u32 s100, s16, 0xb0000
	s_addc_u32 s101, s17, 0
	global_load_dwordx4 v[226:229], v200, s[100:101]
	global_load_dwordx4 v[230:233], v200, s[100:101] offset:16
	global_load_dwordx4 v[234:237], v200, s[100:101] offset:512
	global_load_dwordx4 v[238:241], v200, s[100:101] offset:528
	s_waitcnt vmcnt(12)
	v_pk_fma_f32 v[54:55], s[18:19], v[54:55], v[114:115]
	v_pk_fma_f32 v[56:57], s[24:25], v[56:57], v[116:117]
	v_pk_fma_f32 v[50:51], s[18:19], v[50:51], v[118:119]
	v_pk_fma_f32 v[52:53], s[24:25], v[52:53], v[120:121]
	v_pk_fma_f32 v[58:59], s[18:19], v[58:59], v[122:123]
	v_pk_fma_f32 v[60:61], s[24:25], v[60:61], v[124:125]
	v_pk_fma_f32 v[62:63], s[18:19], v[62:63], v[126:127]
	v_pk_fma_f32 v[64:65], s[24:25], v[64:65], v[128:129]
	v_mul_f32_e32 v202, v57, v57
	v_mul_f32_e32 v201, v55, v55
	v_fmac_f32_e32 v201, v54, v54
	v_fmac_f32_e32 v202, v56, v56
	v_add_f32_e32 v201, v201, v202
	v_mul_f32_e32 v206, v53, v53
	v_mul_f32_e32 v203, v51, v51
	v_fmac_f32_e32 v203, v50, v50
	v_fmac_f32_e32 v206, v52, v52
	v_add_f32_e32 v203, v203, v206
	v_add_f32_e32 v201, v201, v203
	v_mul_f32_e32 v206, v61, v61
	v_mul_f32_e32 v203, v59, v59
	v_fmac_f32_e32 v203, v58, v58
	v_fmac_f32_e32 v206, v60, v60
	v_add_f32_e32 v203, v203, v206
	v_mul_f32_e32 v206, v65, v65
	v_mul_f32_e32 v202, v63, v63
	v_fmac_f32_e32 v202, v62, v62
	v_fmac_f32_e32 v206, v64, v64
	v_add_f32_e32 v202, v202, v206
	v_add_f32_e32 v203, v203, v202
	v_add_f32_e32 v246, v201, v203
	s_waitcnt vmcnt(8)
	v_pk_fma_f32 v[38:39], s[18:19], v[38:39], v[98:99]
	v_pk_fma_f32 v[40:41], s[24:25], v[40:41], v[100:101]
	v_pk_fma_f32 v[34:35], s[18:19], v[34:35], v[102:103]
	v_pk_fma_f32 v[36:37], s[24:25], v[36:37], v[104:105]
	v_pk_fma_f32 v[42:43], s[18:19], v[42:43], v[106:107]
	v_pk_fma_f32 v[44:45], s[24:25], v[44:45], v[108:109]
	v_pk_fma_f32 v[46:47], s[18:19], v[46:47], v[110:111]
	v_pk_fma_f32 v[48:49], s[24:25], v[48:49], v[112:113]
	v_mul_f32_e32 v202, v41, v41
	v_mul_f32_e32 v201, v39, v39
	v_fmac_f32_e32 v201, v38, v38
	v_fmac_f32_e32 v202, v40, v40
	v_add_f32_e32 v201, v201, v202
	v_mul_f32_e32 v206, v37, v37
	v_mul_f32_e32 v203, v35, v35
	v_fmac_f32_e32 v203, v34, v34
	v_fmac_f32_e32 v206, v36, v36
	v_add_f32_e32 v203, v203, v206
	v_add_f32_e32 v201, v201, v203
	v_mul_f32_e32 v206, v45, v45
	v_mul_f32_e32 v203, v43, v43
	v_fmac_f32_e32 v203, v42, v42
	v_fmac_f32_e32 v206, v44, v44
	v_add_f32_e32 v203, v203, v206
	v_mul_f32_e32 v206, v49, v49
	v_mul_f32_e32 v202, v47, v47
	v_fmac_f32_e32 v202, v46, v46
	v_fmac_f32_e32 v206, v48, v48
	v_add_f32_e32 v202, v202, v206
	v_add_f32_e32 v203, v203, v202
	v_add_f32_e32 v247, v201, v203
	s_waitcnt vmcnt(4)
	v_pk_fma_f32 v[22:23], s[18:19], v[22:23], v[210:211]
	v_pk_fma_f32 v[24:25], s[24:25], v[24:25], v[212:213]
	v_pk_fma_f32 v[18:19], s[18:19], v[18:19], v[214:215]
	v_pk_fma_f32 v[20:21], s[24:25], v[20:21], v[216:217]
	v_pk_fma_f32 v[26:27], s[18:19], v[26:27], v[218:219]
	v_pk_fma_f32 v[28:29], s[24:25], v[28:29], v[220:221]
	v_pk_fma_f32 v[30:31], s[18:19], v[30:31], v[222:223]
	v_pk_fma_f32 v[32:33], s[24:25], v[32:33], v[224:225]
	v_mul_f32_e32 v202, v25, v25
	v_mul_f32_e32 v201, v23, v23
	v_fmac_f32_e32 v201, v22, v22
	v_fmac_f32_e32 v202, v24, v24
	v_add_f32_e32 v201, v201, v202
	v_mul_f32_e32 v206, v21, v21
	v_mul_f32_e32 v203, v19, v19
	v_fmac_f32_e32 v203, v18, v18
	v_fmac_f32_e32 v206, v20, v20
	v_add_f32_e32 v203, v203, v206
	v_add_f32_e32 v201, v201, v203
	v_mul_f32_e32 v206, v29, v29
	v_mul_f32_e32 v203, v27, v27
	v_fmac_f32_e32 v203, v26, v26
	v_fmac_f32_e32 v206, v28, v28
	v_add_f32_e32 v203, v203, v206
	v_mul_f32_e32 v206, v33, v33
	v_mul_f32_e32 v202, v31, v31
	v_fmac_f32_e32 v202, v30, v30
	v_fmac_f32_e32 v206, v32, v32
	v_add_f32_e32 v202, v202, v206
	v_add_f32_e32 v203, v203, v202
	v_add_f32_e32 v248, v201, v203
	s_waitcnt vmcnt(0)
	v_pk_fma_f32 v[6:7], s[18:19], v[6:7], v[226:227]
	v_pk_fma_f32 v[8:9], s[24:25], v[8:9], v[228:229]
	v_pk_fma_f32 v[2:3], s[18:19], v[2:3], v[230:231]
	v_pk_fma_f32 v[4:5], s[24:25], v[4:5], v[232:233]
	v_pk_fma_f32 v[10:11], s[18:19], v[10:11], v[234:235]
	v_pk_fma_f32 v[12:13], s[24:25], v[12:13], v[236:237]
	v_pk_fma_f32 v[14:15], s[18:19], v[14:15], v[238:239]
	v_pk_fma_f32 v[16:17], s[24:25], v[16:17], v[240:241]
	v_mul_f32_e32 v202, v9, v9
	v_mul_f32_e32 v201, v7, v7
	v_fmac_f32_e32 v201, v6, v6
	v_fmac_f32_e32 v202, v8, v8
	v_add_f32_e32 v201, v201, v202
	v_mul_f32_e32 v206, v5, v5
	v_mul_f32_e32 v203, v3, v3
	v_fmac_f32_e32 v203, v2, v2
	v_fmac_f32_e32 v206, v4, v4
	v_add_f32_e32 v203, v203, v206
	v_add_f32_e32 v201, v201, v203
	v_mul_f32_e32 v206, v13, v13
	v_mul_f32_e32 v203, v11, v11
	v_fmac_f32_e32 v203, v10, v10
	v_fmac_f32_e32 v206, v12, v12
	v_add_f32_e32 v203, v203, v206
	v_mul_f32_e32 v206, v17, v17
	v_mul_f32_e32 v202, v15, v15
	v_fmac_f32_e32 v202, v14, v14
	v_fmac_f32_e32 v206, v16, v16
	v_add_f32_e32 v202, v202, v206
	v_add_f32_e32 v203, v203, v202
	v_add_f32_e32 v249, v201, v203
	ds_bpermute_b32 v168, v0, v242
	ds_bpermute_b32 v169, v0, v243
	ds_bpermute_b32 v170, v0, v244
	ds_bpermute_b32 v171, v0, v245
	ds_bpermute_b32 v172, v0, v246
	ds_bpermute_b32 v173, v0, v247
	ds_bpermute_b32 v174, v0, v248
	ds_bpermute_b32 v175, v0, v249
	s_waitcnt lgkmcnt(0)
	v_add_f32_e32 v242, v242, v168
	v_add_f32_e32 v243, v243, v169
	v_add_f32_e32 v244, v244, v170
	v_add_f32_e32 v245, v245, v171
	v_add_f32_e32 v246, v246, v172
	v_add_f32_e32 v247, v247, v173
	v_add_f32_e32 v248, v248, v174
	v_add_f32_e32 v249, v249, v175
	ds_bpermute_b32 v168, v251, v242
	ds_bpermute_b32 v169, v251, v243
	ds_bpermute_b32 v170, v251, v244
	ds_bpermute_b32 v171, v251, v245
	ds_bpermute_b32 v172, v251, v246
	ds_bpermute_b32 v173, v251, v247
	ds_bpermute_b32 v174, v251, v248
	ds_bpermute_b32 v175, v251, v249
	v_lshlrev_b32_e32 v201, 6, v194
	v_add_u32_e32 v202, 0x2000, v201
	s_waitcnt lgkmcnt(0)
	v_add_f32_e32 v242, v242, v168
	v_add_f32_e32 v243, v243, v169
	v_add_f32_e32 v244, v244, v170
	v_add_f32_e32 v245, v245, v171
	v_add_f32_e32 v246, v246, v172
	v_add_f32_e32 v247, v247, v173
	v_add_f32_e32 v248, v248, v174
	v_add_f32_e32 v249, v249, v175
	s_and_saveexec_b64 s[8:9], vcc
	global_store_dword v201, v242, s[6:7]
	global_store_dword v201, v243, s[6:7] offset:1024
	global_store_dword v201, v244, s[6:7] offset:2048
	global_store_dword v201, v245, s[6:7] offset:3072
	global_store_dword v202, v246, s[6:7]
	global_store_dword v202, v247, s[6:7] offset:1024
	global_store_dword v202, v248, s[6:7] offset:2048
	global_store_dword v202, v249, s[6:7] offset:3072
	s_or_b64 exec, exec, s[8:9]
	v_or_b32_e32 v190, 16, v194
	v_ashrrev_i32_e32 v191, 31, v190
	v_lshlrev_b64 v[196:197], 6, v[190:191]
	v_or_b32_e32 v186, 32, v194
	v_ashrrev_i32_e32 v187, 31, v186
	v_lshlrev_b64 v[192:193], 6, v[186:187]
	v_or_b32_e32 v182, 48, v194
	v_ashrrev_i32_e32 v183, 31, v182
	v_lshlrev_b64 v[188:189], 6, v[182:183]
	v_add_u32_e32 v178, 0x80, v194
	v_ashrrev_i32_e32 v179, 31, v178
	v_lshlrev_b64 v[184:185], 6, v[178:179]
	v_add_u32_e32 v174, 0x90, v194
	v_ashrrev_i32_e32 v175, 31, v174
	v_lshlrev_b64 v[180:181], 6, v[174:175]
	v_add_u32_e32 v170, 0xa0, v194
	v_ashrrev_i32_e32 v171, 31, v170
	v_lshlrev_b64 v[176:177], 6, v[170:171]
	v_add_u32_e32 v168, 0xb0, v194
	v_ashrrev_i32_e32 v169, 31, v168
	v_lshlrev_b64 v[172:173], 6, v[168:169]
	v_lshlrev_b64 v[198:199], 6, v[194:195]
	s_getreg_b32 s0, hwreg(HW_REG_XCC_ID, 0, 4)
	s_waitcnt vmcnt(0)
	s_waitcnt lgkmcnt(0)
	s_barrier
	s_mov_b64 s[6:7], exec
	v_readlane_b32 s8, v252, 4
	v_readlane_b32 s9, v252, 5
	s_and_b64 s[8:9], s[6:7], s[8:9]
	s_xor_b64 s[6:7], s[8:9], s[6:7]
	s_mov_b64 exec, s[8:9]
	s_cbranch_execz .LBB0_601
	v_readlane_b32 s8, v253, 9
	s_waitcnt vmcnt(0) expcnt(0) lgkmcnt(0)
	s_and_b32 s0, s0, 15
	v_mov_b32_e32 v0, s8
	ds_read_b32 v99, v0
	v_readlane_b32 s8, v253, 10
	s_waitcnt lgkmcnt(0)
	v_cmp_ne_u32_e32 vcc, 0, v99
	v_mov_b32_e32 v0, s8
	ds_read_b32 v98, v0
	s_cbranch_vccnz .LBB0_564
	s_mov_b32 s14, 1
	s_branch .LBB0_552

	.amdhsa_kernel _Z8yoco_fwd6Params
		.amdhsa_group_segment_fixed_size 0
		.amdhsa_private_segment_fixed_size 0
		.amdhsa_kernarg_size 400
		.amdhsa_user_sgpr_count 2
		.amdhsa_user_sgpr_dispatch_ptr 0
		.amdhsa_user_sgpr_queue_ptr 0
		.amdhsa_user_sgpr_kernarg_segment_ptr 1
		.amdhsa_user_sgpr_dispatch_id 0
		.amdhsa_user_sgpr_kernarg_preload_length 0
		.amdhsa_user_sgpr_kernarg_preload_offset 0
		.amdhsa_user_sgpr_private_segment_size 0
		.amdhsa_uses_dynamic_stack 0
		.amdhsa_enable_private_segment 0
		.amdhsa_system_sgpr_workgroup_id_x 1
		.amdhsa_system_sgpr_workgroup_id_y 0
		.amdhsa_system_sgpr_workgroup_id_z 0
		.amdhsa_system_sgpr_workgroup_info 0
		.amdhsa_system_vgpr_workitem_id 2
		.amdhsa_next_free_vgpr 256
		.amdhsa_next_free_sgpr 102
		.amdhsa_accum_offset 256
		.amdhsa_reserve_vcc 1
		.amdhsa_float_round_mode_32 0
		.amdhsa_float_round_mode_16_64 0
		.amdhsa_float_denorm_mode_32 3
		.amdhsa_float_denorm_mode_16_64 3
		.amdhsa_dx10_clamp 1
		.amdhsa_ieee_mode 1
		.amdhsa_fp16_overflow 0
		.amdhsa_tg_split 0
		.amdhsa_exception_fp_ieee_invalid_op 0
		.amdhsa_exception_fp_denorm_src 0
		.amdhsa_exception_fp_ieee_div_zero 0
		.amdhsa_exception_fp_ieee_overflow 0
		.amdhsa_exception_fp_ieee_underflow 0
		.amdhsa_exception_fp_ieee_inexact 0
		.amdhsa_exception_int_div_zero 0
	.end_amdhsa_kernel

amdhsa.kernels:
  - .agpr_count:     0
    .args:
      - .offset:         0
        .size:           144
        .value_kind:     by_value
      - .offset:         144
        .size:           4
        .value_kind:     hidden_block_count_x
      - .offset:         148
        .size:           4
        .value_kind:     hidden_block_count_y
      - .offset:         152
        .size:           4
        .value_kind:     hidden_block_count_z
      - .offset:         156
        .size:           2
        .value_kind:     hidden_group_size_x
      - .offset:         158
        .size:           2
        .value_kind:     hidden_group_size_y
      - .offset:         160
        .size:           2
        .value_kind:     hidden_group_size_z
      - .offset:         162
        .size:           2
        .value_kind:     hidden_remainder_x
      - .offset:         164
        .size:           2
        .value_kind:     hidden_remainder_y
      - .offset:         166
        .size:           2
        .value_kind:     hidden_remainder_z
      - .offset:         184
        .size:           8
        .value_kind:     hidden_global_offset_x
      - .offset:         192
        .size:           8
        .value_kind:     hidden_global_offset_y
      - .offset:         200
        .size:           8
        .value_kind:     hidden_global_offset_z
      - .offset:         208
        .size:           2
        .value_kind:     hidden_grid_dims
      - .offset:         232
        .size:           8
        .value_kind:     hidden_multigrid_sync_arg
      - .offset:         264
        .size:           4
        .value_kind:     hidden_dynamic_lds_size
    .group_segment_fixed_size: 0
    .kernarg_segment_align: 8
    .kernarg_segment_size: 400
    .language:       OpenCL C
    .language_version:
      - 2
      - 0
    .max_flat_workgroup_size: 512
    .name:           _Z8yoco_fwd6Params
    .private_segment_fixed_size: 0
    .sgpr_count:     108
    .sgpr_spill_count: 265
    .symbol:         _Z8yoco_fwd6Params.kd
    .uniform_work_group_size: 1
    .uses_dynamic_stack: false
    .vgpr_count:     256
    .vgpr_spill_count: 0
    .wavefront_size: 64
